# barrier-3 gap: P3 pointwise-GEMM CUs touch their tile's gate block (SGB) into L2 so the epilogue's gate loads hit L2
# speedup vs baseline: 1.0023x; 1.0023x over previous
.LBB0_592:
	s_or_b64 exec, exec, s[6:7]
	s_cmpk_gt_u32 s2, 0xcb
	s_cbranch_scc1 .Lg3_skip
	s_load_dwordx2 s[10:11], s[0:1], 0xb0
	s_and_b32 s12, s2, 7
	s_lshr_b32 s13, s2, 3
	s_mul_i32 s18, s12, 26
	s_mul_i32 s19, s12, 25
	s_add_i32 s19, s19, 4
	s_cmp_lt_u32 s12, 4
	s_cselect_b32 s18, s18, s19
	s_add_i32 s18, s18, s13
	s_mul_i32 s19, s18, 0x556
	s_lshr_b32 s19, s19, 16
	s_mul_i32 s20, s19, 48
	s_sub_i32 s20, s18, s20
	s_lshl_b32 s19, s19, 3
	s_cmp_eq_u32 s19, 32
	s_cbranch_scc1 .Lg3_tail
	s_and_b32 s12, s20, 7
	s_lshr_b32 s13, s20, 3
	s_branch .Lg3_j
.Lg3_tail:
	s_and_b32 s12, s20, 1
	s_lshr_b32 s13, s20, 1
.Lg3_j:
	s_add_i32 s12, s12, s19
	s_mul_i32 s12, s12, 0xc0000
	s_lshl_b32 s13, s13, 9
	s_add_i32 s12, s12, s13
	v_lshrrev_b32_e32 v250, 2, v0
	v_mul_u32_u24_e32 v250, 0xc00, v250
	v_and_b32_e32 v251, 3, v0
	v_lshl_add_u32 v250, v251, 7, v250
	s_waitcnt lgkmcnt(0)
	s_add_u32 s10, s10, 0x7800000
	s_addc_u32 s11, s11, 0
	s_add_u32 s10, s10, s12
	s_addc_u32 s11, s11, 0
	global_load_dword v252, v250, s[10:11]
	v_add_u32_e32 v251, 0x60000, v250
	global_load_dword v252, v251, s[10:11]
.Lg3_skip:
	v_mov_b32_e32 v1, v0
	s_mov_b64 s[6:7], s[0:1]
	s_load_dwordx2 s[10:11], s[6:7], 0xb0
	s_mov_b64 s[12:13], -1
	s_waitcnt lgkmcnt(0)
	s_add_u32 s29, s10, 0x2100000
	s_addc_u32 s34, s11, 0
	s_cmpk_lt_i32 s2, 0xcc
	s_cselect_b64 s[6:7], -1, 0
	s_cmpk_gt_i32 s2, 0xcb
	s_cbranch_scc1 .LBB0_598
	s_ashr_i32 s18, s2, 31
	s_lshr_b32 s18, s18, 29
	s_add_i32 s18, s2, s18
	s_and_b32 s19, s18, -8
	s_sub_i32 s20, s2, s19
	s_cmp_gt_i32 s20, 3
	s_cbranch_scc0 .LBB0_595
	s_mul_i32 s12, s20, 25
	s_add_i32 s19, s12, 4
	s_mov_b64 s[12:13], 0
